# FFN-up tile order: WGM 2->4 (4 row tiles x 8 col tiles per XCD round; halves weight re-streaming)
# speedup vs baseline: 1.0061x; 1.0036x over previous
;     __host__ __device__ bool next(int i, Unit& u) const {
;         const long L = (long)i * G + c; if (L >= nwg) return false;
;         int wgid = (int)L; { const int q = nwg / NXCD, r = nwg % NXCD, xcd = wgid % NXCD, off = wgid / NXCD; wgid = (xcd < r ? xcd * (q + 1) : r * (q + 1) + (xcd - r) * q) + off; }
;         const int nig = WGM * nN, gid = wgid / nig, fm = gid * WGM, gsz = (nM - fm) < WGM ? (nM - fm) : WGM;
;         u.pm = fm + ((wgid % nig) % gsz); u.pn = (wgid % nig) / gsz; return true;
.LBB0_274:
	s_waitcnt lgkmcnt(0)
	s_lshr_b32 s0, s16, 16
	v_writelane_b32 v254, s0, 7
	s_and_b32 s0, s16, 0xffff
	s_lshl_b32 s2, s82, 3
	s_lshl_b32 s73, s22, 3
	s_cmpk_lt_i32 s82, 0x100
	s_cselect_b64 s[4:5], -1, 0
	s_ashr_i32 s84, s82, 31
	v_writelane_b32 v254, s2, 8
	s_lshr_b32 s2, s84, 29
	s_add_i32 s2, s82, s2
	s_ashr_i32 s6, s2, 3
	s_and_b32 s2, s2, -8
	s_sub_i32 s7, s82, s2
	s_mul_i32 s1, s23, s22
	s_lshl_b32 s2, s7, 5
	s_ashr_i32 s23, s22, 31
	v_writelane_b32 v254, s4, 9
	s_cmpk_lt_i32 s82, 0x400
	v_bfe_u32 v1, v0, 10, 10
	v_writelane_b32 v254, s5, 10
	s_cselect_b64 s[4:5], -1, 0
	v_writelane_b32 v254, s4, 11
	v_bfe_u32 v0, v0, 20, 10
	v_mad_u32_u24 v197, v0, s0, v1
	v_writelane_b32 v254, s5, 12
	s_lshl_b32 s4, s7, 7
	s_lshl_b32 s5, s0, 8
	s_cmp_lt_i32 s82, 6
	v_writelane_b32 v254, s5, 13
	s_cselect_b64 s[8:9], -1, 0
	v_writelane_b32 v254, s8, 14
	s_cmpk_lt_i32 s82, 0xa0
	s_mul_i32 s57, s1, s3
	v_writelane_b32 v254, s9, 15
	s_cselect_b64 s[8:9], -1, 0
	v_writelane_b32 v254, s8, 16
	s_cmpk_lg_i32 s22, 0x100
	v_cvt_f32_u32_e32 v0, s22
	v_writelane_b32 v254, s9, 17
	s_cselect_b64 s[8:9], -1, 0
	v_writelane_b32 v254, s8, 18
	s_add_i32 s5, s82, 0xffffff60
	v_rcp_iflag_f32_e32 v0, v0
	v_writelane_b32 v254, s9, 19
	s_add_i32 s8, s82, 0x80
	s_cmpk_gt_i32 s82, 0x9f
	s_cselect_b32 s5, s5, 0xc0
	s_cmpk_lt_i32 s82, 0x260
	v_writelane_b32 v254, s5, 20
	s_cselect_b64 s[10:11], -1, 0
	s_lshl_b32 s5, s22, 1
	s_sub_i32 s5, 0x260, s5
	v_writelane_b32 v254, s10, 21
	s_cmp_ge_i32 s82, s5
	s_mul_i32 s5, s7, 33
	v_writelane_b32 v254, s11, 22
	s_cselect_b64 s[10:11], -1, 0
	s_cmp_lt_i32 s7, 0
	s_mul_i32 s9, s7, 0x81
	s_cselect_b32 s0, s5, s2
	s_movk_i32 s2, 0x4d
	s_cselect_b32 s1, s9, s4
	s_cselect_b32 s3, 21, 20
	s_cselect_b32 s9, s2, 0x4c
	s_add_i32 s0, s0, s6
	s_ashr_i32 s2, s0, 31
	s_lshr_b32 s2, s2, 28
	s_add_i32 s2, s0, s2
	s_ashr_i32 s4, s2, 4
	s_and_b32 s2, s2, 0xfff0
	s_sub_i32 s2, s0, s2
	s_bfe_u32 s0, s2, 0x10007
	s_add_i32 s5, s2, s0
	s_bfe_i32 s0, s5, 0x80000
	s_and_b32 s5, s5, 0xfe
	v_writelane_b32 v254, s10, 23
	s_sub_i32 s2, s2, s5
	s_lshl_b32 s4, s4, 1
	v_writelane_b32 v254, s11, 24
	s_sext_i32_i16 s10, s0
	s_sext_i32_i8 s2, s2
	s_add_i32 s12, s4, s2
	s_ashr_i32 s2, s10, 1
	s_add_i32 s1, s1, s6
	v_writelane_b32 v254, s2, 25
	s_ashr_i32 s2, s1, 31
	s_lshr_b32 s2, s2, 25
	s_add_i32 s2, s1, s2
	s_ashr_i32 s4, s2, 7
	s_and_b32 s2, s2, 0xff80
	s_sub_i32 s1, s1, s2
	s_bfe_u32 s2, s1, 0x10007
	s_add_i32 s5, s1, s2
	s_bfe_i32 s2, s5, 0x80000
	s_and_b32 s5, s5, 0xfc
	s_sub_i32 s1, s1, s5
	s_lshr_b32 s0, s10, 1
	s_lshl_b32 s4, s4, 2
	s_sext_i32_i16 s10, s2
	s_sext_i32_i8 s1, s1
	s_mul_i32 s3, s7, s3
	s_add_i32 s14, s4, s1
	s_ashr_i32 s1, s10, 2
	s_add_i32 s3, s3, s6
	v_writelane_b32 v254, s1, 26
	s_mul_hi_i32 s1, s3, 0x66666667
	s_lshr_b32 s4, s1, 31
	s_ashr_i32 s1, s1, 2
	s_add_i32 s1, s1, s4
	s_mul_i32 s4, s1, 10
	s_sub_i32 s3, s3, s4
	s_bfe_u32 s4, s3, 0x10007
	s_add_i32 s5, s3, s4
	s_bfe_i32 s4, s5, 0x80000
	s_and_b32 s5, s5, 0xfe
	s_sub_i32 s3, s3, s5
	s_lshl_b32 s1, s1, 1
	s_sext_i32_i8 s3, s3
	s_lshr_b32 s2, s10, 2
	s_sext_i32_i16 s10, s4
	s_add_i32 s1, s1, s3
	s_lshr_b32 s4, s10, 1
	v_writelane_b32 v254, s1, 27
	s_ashr_i32 s1, s10, 1
	v_writelane_b32 v254, s1, 28
	s_bfe_i64 s[4:5], s[4:5], 0x100000
	s_mul_i32 s1, s7, s9
	s_lshl_b64 s[4:5], s[4:5], 18
	s_add_i32 s1, s1, s6
	v_writelane_b32 v254, s4, 29
	s_mul_hi_i32 s3, s1, 0x6bca1af3
	s_ashr_i32 s13, s12, 31
	v_writelane_b32 v254, s5, 30
	s_lshr_b32 s4, s3, 31
	s_ashr_i32 s3, s3, 4
	s_add_i32 s3, s3, s4
	s_lshl_b32 s5, s3, 1
	s_mul_i32 s3, s3, 38
	s_sub_i32 s1, s1, s3
	s_bfe_u32 s3, s1, 0x10007
	s_add_i32 s3, s1, s3
	s_bfe_i32 s4, s3, 0x80000
	s_and_b32 s3, s3, 0xfe
	s_sub_i32 s1, s1, s3
	s_sext_i32_i16 s6, s4
	s_sext_i32_i8 s1, s1
;     __host__ __device__ bool next(int i, Unit& u) const {
;         const long L = (long)i * G + c; if (L >= nwg) return false;
;         int wgid = (int)L; { const int q = nwg / NXCD, r = nwg % NXCD, xcd = wgid % NXCD, off = wgid / NXCD; wgid = (xcd < r ? xcd * (q + 1) : r * (q + 1) + (xcd - r) * q) + off; }
;         const int nig = WGM * nN, gid = wgid / nig, fm = gid * WGM, gsz = (nM - fm) < WGM ? (nM - fm) : WGM;
;         u.pm = fm + ((wgid % nig) % gsz); u.pn = (wgid % nig) / gsz; return true;
; template <class Epi, class Sched, bool ALIGN_EPI = false, bool SP2 = false>
; __device__ __forceinline__ void gemm_phase(PG8_LAS unsigned char* lds, const Gemm g, const Sched& S, const Epi& E) {
;     ...
;     const char* cA = (const char*)g.A + (size_t)cur.pm * tstepA; const char* cB = (const char*)g.Bt + (size_t)cur.pn * tstepB;
	s_add_i32 s10, s5, s1
	s_ashr_i32 s1, s6, 1
	s_lshr_b32 s4, s6, 1
	v_writelane_b32 v254, s1, 31
	s_lshl_b64 s[6:7], s[12:13], 22
	v_writelane_b32 v254, s6, 32
	s_bfe_i64 s[0:1], s[0:1], 0x100000
	s_ashr_i32 s15, s14, 31
	v_writelane_b32 v254, s7, 33
	s_lshl_b64 s[6:7], s[0:1], 22
	v_writelane_b32 v254, s6, 34
	s_bfe_i64 s[2:3], s[2:3], 0x100000
	s_lshl_b64 s[2:3], s[2:3], 20
	v_writelane_b32 v254, s7, 35
	s_mov_b32 s6, s14
	v_writelane_b32 v254, s6, 36
	s_lshl_b64 s[0:1], s[0:1], 20
	s_ashr_i32 s11, s10, 31
	v_writelane_b32 v254, s7, 37
	s_lshl_b64 s[6:7], s[14:15], 20
	v_writelane_b32 v254, s6, 38
	v_mul_f32_e32 v0, 0x4f7ffffe, v0
	v_cvt_u32_f32_e32 v0, v0
	v_writelane_b32 v254, s7, 39
	v_writelane_b32 v254, s2, 40
	s_movk_i32 s89, 0xc00
	s_movk_i32 s81, 0x2600
	v_writelane_b32 v254, s3, 41
	s_mov_b32 s2, s12
	v_writelane_b32 v254, s2, 42
	s_mov_b32 s17, 0x10000
	v_mov_b32_e32 v1, 0
	v_writelane_b32 v254, s3, 43
	s_lshl_b64 s[2:3], s[12:13], 20
	v_writelane_b32 v254, s2, 44
	s_mov_b32 s24, 0x14000
	s_movk_i32 s86, 0x4000
	v_writelane_b32 v254, s3, 45
	v_writelane_b32 v254, s0, 46
	s_movk_i32 s3, 0xa00
	s_movk_i32 s93, 0x60
	v_writelane_b32 v254, s1, 47
	s_mov_b32 s0, s10
	v_writelane_b32 v254, s0, 48
	s_mov_b32 s87, 0x18000
	s_mov_b32 s74, 0x8000
	v_writelane_b32 v254, s1, 49
	s_lshl_b64 s[0:1], s[10:11], 20
	v_writelane_b32 v254, s0, 50
	s_mov_b32 s69, 0x1c000
	s_mov_b32 s78, 0xc000
	v_writelane_b32 v254, s1, 51
	s_bfe_i64 s[0:1], s[4:5], 0x100000
	s_lshl_b64 s[0:1], s[0:1], 20
	v_writelane_b32 v254, s0, 52
	v_mov_b32_e32 v198, 0x358637bd
	s_mov_b32 s16, 0x800000
	v_writelane_b32 v254, s1, 53
	s_sub_i32 s0, 0, s22
	v_readfirstlane_b32 s1, v0
	s_mul_i32 s0, s0, s1
	s_mul_hi_u32 s0, s1, s0
	s_add_i32 s1, s1, s0
	s_mul_hi_u32 s0, s8, s1
	s_mul_i32 s0, s0, s22
	s_sub_i32 s0, s8, s0
	s_sub_i32 s1, s0, s22
	s_cmp_ge_u32 s0, s22
	s_cselect_b32 s0, s1, s0
	s_sub_i32 s1, s0, s22
	s_cmp_ge_u32 s0, s22
	s_cselect_b32 s0, s1, s0
	v_writelane_b32 v254, s0, 54
	s_mul_i32 s0, s22, 0x6000
	s_mul_hi_i32 s1, s73, 0xc00
	v_writelane_b32 v254, s0, 55
	v_mov_b32_e32 v199, 0x2000
	v_mbcnt_lo_u32_b32 v0, -1, 0
	v_writelane_b32 v254, s1, 56
	s_mul_i32 s0, s22, 0x5000
	s_mul_hi_i32 s1, s73, 0xa00
	v_writelane_b32 v254, s0, 57
	v_mov_b32_e32 v216, 1
	v_mov_b64_e32 v[200:201], 0x100
	v_writelane_b32 v254, s1, 58
	s_lshl_b32 s0, s82, 8
	v_writelane_b32 v254, s0, 59
	s_lshl_b32 s0, s22, 8
	v_writelane_b32 v254, s0, 60
	s_mul_i32 s0, s22, 0x13000
	v_writelane_b32 v254, s0, 61
	s_lshl_b32 s0, s82, 6
	v_writelane_b32 v254, s0, 62
	s_lshl_b32 s0, s22, 6
	v_writelane_b32 v254, s0, 63
	s_mov_b32 s0, 0x20fc0
	s_add_i32 s88, s0, 0x100
	s_mov_b32 s0, 0x20080
	s_addk_i32 s0, 0x100
	v_writelane_b32 v255, s0, 0
	s_mov_b32 s0, 0x20084
	s_addk_i32 s0, 0x100
	v_writelane_b32 v255, s0, 1
	v_writelane_b32 v255, s73, 2
	v_writelane_b32 v255, s84, 3
	v_mov_b64_e32 v[202:203], 0xff
	v_mbcnt_hi_u32_b32 v217, -1, v0
	v_mov_b32_e32 v218, 0x7f800000
	v_mov_b32_e32 v219, 0xff800000
	v_mov_b32_e32 v220, 0x840
	v_mov_b32_e32 v221, 0x1080
	v_mov_b32_e32 v253, 0x100
	v_bfrev_b32_e32 v226, 40
	v_mov_b32_e32 v204, 0x3f317218
	v_mov_b64_e32 v[206:207], 0x260
	v_mov_b64_e32 v[208:209], 0x25f
	s_mov_b32 s79, 0x2aaaaaab
	s_mov_b32 s75, 0x41000000
	s_mov_b32 s83, 0x30000
	s_mov_b32 s68, 0x60000
	s_mov_b32 s70, 0x20000
	s_mov_b32 s72, 0x24000
	s_mov_b32 s60, 0x2c000
	s_mov_b32 s91, 0x6c000
	s_mov_b32 s56, 0x70000
	s_movk_i32 s71, 0x1246
	s_movk_i32 s54, 0x4918
	s_movk_i32 s25, 0xf05
	s_movk_i32 s55, 0xeff
	s_mov_b64 s[94:95], 0x80
	s_mov_b64 s[96:97], 0x100
	s_mov_b32 s80, 0x3dd53b94
	s_mov_b32 s92, 0x3e0293ee
	s_mov_b32 s90, 0x3e38aa3b
	s_mov_b32 s34, 0x3b000000
	s_mov_b32 s37, 0
	v_writelane_b32 v255, s57, 4
	s_branch .LBB0_278

;     __host__ __device__ bool next(int i, Unit& u) const {
;         const long L = (long)i * G + c; if (L >= nwg) return false;
;         int wgid = (int)L; { const int q = nwg / NXCD, r = nwg % NXCD, xcd = wgid % NXCD, off = wgid / NXCD; wgid = (xcd < r ? xcd * (q + 1) : r * (q + 1) + (xcd - r) * q) + off; }
;         const int nig = WGM * nN, gid = wgid / nig, fm = gid * WGM, gsz = (nM - fm) < WGM ? (nM - fm) : WGM;
;         u.pm = fm + ((wgid % nig) % gsz); u.pn = (wgid % nig) / gsz; return true;
; template <class Epi, class Sched, bool ALIGN_EPI = false, bool SP2 = false>
; __device__ __forceinline__ void gemm_phase(PG8_LAS unsigned char* lds, const Gemm g, const Sched& S, const Epi& E) {
;     ...
;         const bool has_next = S.next(ui + 1, nxt);
;         const char* nA = has_next ? (const char*)g.A + (size_t)nxt.pm * tstepA : cA; const char* nB = has_next ? (const char*)g.Bt + (size_t)nxt.pn * tstepB : cB;
.LBB0_413:
	s_ashr_i32 s2, s2, 3
	s_add_i32 s2, s38, s2
	s_ashr_i32 s26, s2, 31
	s_lshr_b32 s26, s26, 25
	s_add_i32 s26, s2, s26
	s_ashr_i32 s27, s26, 7
	s_lshl_b32 s27, s27, 2
	s_sub_i32 s33, 32, s27
	s_min_i32 s33, s33, 4
	s_abs_i32 s38, s33
	v_cvt_f32_u32_e32 v2, s38
	s_sub_i32 s40, 0, s38
	s_andn2_b32 s26, s26, 127
	s_sub_i32 s2, s2, s26
	v_rcp_iflag_f32_e32 v2, v2
	s_abs_i32 s26, s2
	s_xor_b32 s39, s2, s33
	s_ashr_i32 s39, s39, 31
	v_mul_f32_e32 v2, 0x4f7ffffe, v2
	v_cvt_u32_f32_e32 v2, v2
	s_nop 0
	v_readfirstlane_b32 s41, v2
	s_mul_i32 s40, s40, s41
	s_mul_hi_u32 s40, s41, s40
	s_add_i32 s41, s41, s40
	s_mul_hi_u32 s40, s26, s41
	s_mul_i32 s41, s40, s38
	s_sub_i32 s26, s26, s41
	s_add_i32 s42, s40, 1
	s_sub_i32 s41, s26, s38
	s_cmp_ge_u32 s26, s38
	s_cselect_b32 s40, s42, s40
	s_cselect_b32 s26, s41, s26
	s_add_i32 s41, s40, 1
	s_cmp_ge_u32 s26, s38
	s_cselect_b32 s26, s41, s40
	s_xor_b32 s26, s26, s39
	s_sub_i32 s26, s26, s39
	s_mul_i32 s33, s26, s33
	s_sub_i32 s2, s2, s33
	s_add_i32 s38, s27, s2
